# ping-pong attention + MFMA-phase priority; all 16 P conversions moved into the VALU phase (in place), first V bank read ahead of the QK MFMAs into dead score registers
# speedup vs baseline: 1.0057x; 1.0006x over previous
.LBB0_1183:
	s_andn2_b64 s[42:43], exec, s[70:71]
	v_exp_f32_e32 v96, v96
	v_exp_f32_e32 v80, v80
	v_exp_f32_e32 v97, v97
	v_exp_f32_e32 v81, v81
	v_add_f32_e32 v9, 0, v96
	v_exp_f32_e32 v98, v98
	v_add_f32_e32 v9, v80, v9
	v_exp_f32_e32 v82, v82
	v_add_f32_e32 v9, v97, v9
	v_exp_f32_e32 v99, v99
	v_add_f32_e32 v9, v81, v9
	v_exp_f32_e32 v83, v83
	v_add_f32_e32 v9, v98, v9
	v_exp_f32_e32 v100, v100
	v_add_f32_e32 v9, v82, v9
	v_exp_f32_e32 v84, v84
	v_add_f32_e32 v9, v99, v9
	v_exp_f32_e32 v101, v101
	v_add_f32_e32 v9, v83, v9
	v_exp_f32_e32 v85, v85
	v_add_f32_e32 v9, v100, v9
	v_exp_f32_e32 v102, v102
	v_add_f32_e32 v9, v84, v9
	v_exp_f32_e32 v86, v86
	v_add_f32_e32 v9, v101, v9
	v_exp_f32_e32 v103, v103
	v_add_f32_e32 v9, v85, v9
	v_exp_f32_e32 v87, v87
	v_add_f32_e32 v9, v102, v9
	v_exp_f32_e32 v104, v104
	v_add_f32_e32 v9, v86, v9
	v_exp_f32_e32 v88, v88
	v_add_f32_e32 v9, v103, v9
	v_exp_f32_e32 v105, v105
	v_add_f32_e32 v9, v87, v9
	v_exp_f32_e32 v89, v89
	v_add_f32_e32 v9, v104, v9
	v_exp_f32_e32 v106, v106
	v_add_f32_e32 v9, v88, v9
	v_exp_f32_e32 v90, v90
	v_add_f32_e32 v9, v105, v9
	v_exp_f32_e32 v107, v107
	v_add_f32_e32 v9, v89, v9
	v_exp_f32_e32 v91, v91
	v_add_f32_e32 v9, v106, v9
	v_exp_f32_e32 v108, v108
	v_add_f32_e32 v9, v90, v9
	v_exp_f32_e32 v92, v92
	v_add_f32_e32 v9, v107, v9
	v_exp_f32_e32 v109, v109
	v_add_f32_e32 v9, v91, v9
	v_exp_f32_e32 v93, v93
	v_add_f32_e32 v9, v108, v9
	v_exp_f32_e32 v110, v110
	v_add_f32_e32 v9, v92, v9
	v_exp_f32_e32 v94, v94
	v_add_f32_e32 v9, v109, v9
	v_exp_f32_e32 v111, v111
	v_add_f32_e32 v9, v93, v9
	v_exp_f32_e32 v95, v95
	v_add_f32_e32 v9, v110, v9
	v_add_f32_e32 v9, v94, v9
	v_add_f32_e32 v9, v111, v9
	v_add_f32_e32 v9, v95, v9
	v_add_f32_e32 v161, v161, v9
	v_cvt_pk_bf16_f32 v96, v96, v97
	v_cvt_pk_bf16_f32 v97, v98, v99
	v_cvt_pk_bf16_f32 v98, v100, v101
	v_cvt_pk_bf16_f32 v99, v102, v103
	v_cvt_pk_bf16_f32 v100, v104, v105
	v_cvt_pk_bf16_f32 v101, v106, v107
	v_cvt_pk_bf16_f32 v102, v108, v109
	v_cvt_pk_bf16_f32 v103, v110, v111
	v_cvt_pk_bf16_f32 v80, v80, v81
	v_cvt_pk_bf16_f32 v81, v82, v83
	v_cvt_pk_bf16_f32 v82, v84, v85
	v_cvt_pk_bf16_f32 v83, v86, v87
	v_cvt_pk_bf16_f32 v84, v88, v89
	v_cvt_pk_bf16_f32 v85, v90, v91
	v_cvt_pk_bf16_f32 v86, v92, v93
	v_cvt_pk_bf16_f32 v87, v94, v95
	s_cmp_lg_u32 s19, 0
	s_cbranch_scc1 .Lpp_x0
	s_waitcnt vmcnt(0)

.Lpp_a0_done:
	ds_read_b64_tr_b16 v[104:105], v166 offset:32768
	ds_read_b64_tr_b16 v[106:107], v158 offset:32768
	ds_read_b64_tr_b16 v[108:109], v167 offset:32768
	ds_read_b64_tr_b16 v[110:111], v160 offset:32768
	ds_read_b64_tr_b16 v[88:89], v168 offset:32768
	ds_read_b64_tr_b16 v[90:91], v162 offset:32768
	ds_read_b64_tr_b16 v[92:93], v169 offset:32768
	ds_read_b64_tr_b16 v[94:95], v163 offset:32768
	s_setprio 2
	s_andn2_b64 vcc, exec, s[70:71]
	s_cbranch_vccnz .LBB0_1185
	ds_read_b128 v[0:3], v154 offset:16384
	ds_read_b128 v[4:7], v154 offset:24576
	ds_read_b128 v[170:173], v155 offset:16384
	ds_read_b128 v[174:177], v155 offset:24576
	ds_read_b128 v[182:185], v156 offset:16384
	ds_read_b128 v[186:189], v156 offset:24576
	ds_read_b128 v[194:197], v157 offset:16384
	ds_read_b128 v[226:229], v157 offset:24576
	s_waitcnt lgkmcnt(6)
	v_mfma_f32_32x32x16_bf16 v[128:143], v[0:3], v[238:241], 0
	v_mfma_f32_32x32x16_bf16 v[112:127], v[4:7], v[238:241], 0
	s_waitcnt lgkmcnt(4)
	v_mfma_f32_32x32x16_bf16 v[128:143], v[170:173], v[242:245], v[128:143]
	v_mfma_f32_32x32x16_bf16 v[112:127], v[174:177], v[242:245], v[112:127]
	s_waitcnt lgkmcnt(2)
	v_mfma_f32_32x32x16_bf16 v[128:143], v[182:185], v[246:249], v[128:143]
	v_mfma_f32_32x32x16_bf16 v[112:127], v[186:189], v[246:249], v[112:127]
	s_waitcnt lgkmcnt(0)
	v_mfma_f32_32x32x16_bf16 v[128:143], v[194:197], v[234:237], v[128:143]
	v_mfma_f32_32x32x16_bf16 v[112:127], v[226:229], v[234:237], v[112:127]
.LBB0_1185:
	ds_read_b64_tr_b16 v[178:179], v166 offset:36864
	ds_read_b64_tr_b16 v[180:181], v158 offset:36864
	ds_read_b64_tr_b16 v[182:183], v167 offset:36864
	ds_read_b64_tr_b16 v[184:185], v160 offset:36864
	ds_read_b64_tr_b16 v[186:187], v168 offset:36864
	ds_read_b64_tr_b16 v[188:189], v162 offset:36864
	ds_read_b64_tr_b16 v[190:191], v169 offset:36864
	ds_read_b64_tr_b16 v[192:193], v163 offset:36864
	s_waitcnt lgkmcnt(14)
	s_nop 0
	v_mfma_f32_32x32x16_bf16 v[48:63], v[104:107], v[96:99], v[48:63]
	s_waitcnt lgkmcnt(12)
	v_mfma_f32_32x32x16_bf16 v[64:79], v[108:111], v[96:99], v[64:79]
	s_waitcnt lgkmcnt(10)
	v_mfma_f32_32x32x16_bf16 v[32:47], v[88:91], v[96:99], v[32:47]
	s_waitcnt lgkmcnt(8)
	v_mfma_f32_32x32x16_bf16 v[16:31], v[92:95], v[96:99], v[16:31]
	ds_read_b64_tr_b16 v[0:1], v166 offset:40960
	ds_read_b64_tr_b16 v[2:3], v158 offset:40960
	ds_read_b64_tr_b16 v[4:5], v167 offset:40960
	ds_read_b64_tr_b16 v[6:7], v160 offset:40960
	ds_read_b64_tr_b16 v[10:11], v168 offset:40960
	ds_read_b64_tr_b16 v[12:13], v162 offset:40960
	ds_read_b64_tr_b16 v[174:175], v169 offset:40960
	ds_read_b64_tr_b16 v[176:177], v163 offset:40960
	s_waitcnt lgkmcnt(14)
	s_nop 0
	v_mfma_f32_32x32x16_bf16 v[48:63], v[178:181], v[100:103], v[48:63]
	s_waitcnt lgkmcnt(12)
	v_mfma_f32_32x32x16_bf16 v[64:79], v[182:185], v[100:103], v[64:79]
	s_waitcnt lgkmcnt(10)
	v_mfma_f32_32x32x16_bf16 v[32:47], v[186:189], v[100:103], v[32:47]
	s_waitcnt lgkmcnt(8)
	v_mfma_f32_32x32x16_bf16 v[16:31], v[190:193], v[100:103], v[16:31]
	ds_read_b64_tr_b16 v[178:179], v166 offset:45056
	ds_read_b64_tr_b16 v[180:181], v158 offset:45056
	ds_read_b64_tr_b16 v[182:183], v167 offset:45056
	ds_read_b64_tr_b16 v[184:185], v160 offset:45056
	ds_read_b64_tr_b16 v[186:187], v168 offset:45056
	ds_read_b64_tr_b16 v[188:189], v162 offset:45056
	ds_read_b64_tr_b16 v[190:191], v169 offset:45056
	ds_read_b64_tr_b16 v[192:193], v163 offset:45056
	s_waitcnt lgkmcnt(14)
	s_nop 0
	v_mfma_f32_32x32x16_bf16 v[48:63], v[0:3], v[80:83], v[48:63]
	s_waitcnt lgkmcnt(12)
	v_mfma_f32_32x32x16_bf16 v[64:79], v[4:7], v[80:83], v[64:79]
	s_waitcnt lgkmcnt(10)
	v_mfma_f32_32x32x16_bf16 v[32:47], v[10:13], v[80:83], v[32:47]
	s_waitcnt lgkmcnt(8)
	v_mfma_f32_32x32x16_bf16 v[16:31], v[174:177], v[80:83], v[16:31]
	s_cmp_eq_u32 s19, 0
	s_waitcnt lgkmcnt(0)
	s_cbranch_scc1 .Lpp_y0
	s_waitcnt vmcnt(0)
.Lpp_y0:
	s_barrier
	s_setprio 0
	s_waitcnt lgkmcnt(6)
	v_mfma_f32_32x32x16_bf16 v[48:63], v[178:181], v[84:87], v[48:63]
	s_and_b64 vcc, exec, s[42:43]
	s_waitcnt lgkmcnt(4)
	v_mfma_f32_32x32x16_bf16 v[64:79], v[182:185], v[84:87], v[64:79]
	s_waitcnt lgkmcnt(2)
	v_mfma_f32_32x32x16_bf16 v[32:47], v[186:189], v[84:87], v[32:47]
	s_waitcnt lgkmcnt(0)
	v_mfma_f32_32x32x16_bf16 v[16:31], v[190:193], v[84:87], v[16:31]
	s_cbranch_vccnz .LBB0_1197
	s_andn2_b64 s[42:43], exec, s[68:69]
	s_cmp_eq_u32 s19, 0
	s_cbranch_scc1 .LBB0_1188
	s_add_i32 s3, s74, 3
	s_cmp_ge_u32 s3, s17
	s_cbranch_scc1 .Lpp_b1_v
	s_mov_b32 m0, s27
	s_nop 0
	global_load_lds_dwordx4 v150, s[62:63]
	s_add_i32 m0, s27, 0x400
	s_nop 0
	global_load_lds_dwordx4 v144, s[62:63]

.LBB0_1194:
	v_exp_f32_e32 v128, v128
	v_exp_f32_e32 v112, v112
	v_exp_f32_e32 v129, v129
	v_exp_f32_e32 v113, v113
	v_add_f32_e32 v9, 0, v128
	v_exp_f32_e32 v130, v130
	v_add_f32_e32 v9, v112, v9
	v_exp_f32_e32 v114, v114
	v_add_f32_e32 v9, v129, v9
	v_exp_f32_e32 v131, v131
	v_add_f32_e32 v9, v113, v9
	v_exp_f32_e32 v115, v115
	v_add_f32_e32 v9, v130, v9
	v_exp_f32_e32 v132, v132
	v_add_f32_e32 v9, v114, v9
	v_exp_f32_e32 v116, v116
	v_add_f32_e32 v9, v131, v9
	v_exp_f32_e32 v133, v133
	v_add_f32_e32 v9, v115, v9
	v_exp_f32_e32 v117, v117
	v_add_f32_e32 v9, v132, v9
	v_exp_f32_e32 v134, v134
	v_add_f32_e32 v9, v116, v9
	v_exp_f32_e32 v118, v118
	v_add_f32_e32 v9, v133, v9
	v_exp_f32_e32 v135, v135
	v_add_f32_e32 v9, v117, v9
	v_exp_f32_e32 v119, v119
	v_add_f32_e32 v9, v134, v9
	v_exp_f32_e32 v136, v136
	v_add_f32_e32 v9, v118, v9
	v_exp_f32_e32 v120, v120
	v_add_f32_e32 v9, v135, v9
	v_exp_f32_e32 v137, v137
	v_add_f32_e32 v9, v119, v9
	v_exp_f32_e32 v121, v121
	v_add_f32_e32 v9, v136, v9
	v_exp_f32_e32 v138, v138
	v_add_f32_e32 v9, v120, v9
	v_exp_f32_e32 v122, v122
	v_add_f32_e32 v9, v137, v9
	v_exp_f32_e32 v139, v139
	v_add_f32_e32 v9, v121, v9
	v_exp_f32_e32 v123, v123
	v_add_f32_e32 v9, v138, v9
	v_exp_f32_e32 v140, v140
	v_add_f32_e32 v9, v122, v9
	v_exp_f32_e32 v124, v124
	v_add_f32_e32 v9, v139, v9
	v_exp_f32_e32 v141, v141
	v_add_f32_e32 v9, v123, v9
	v_exp_f32_e32 v125, v125
	v_add_f32_e32 v9, v140, v9
	v_exp_f32_e32 v142, v142
	v_add_f32_e32 v9, v124, v9
	v_exp_f32_e32 v126, v126
	v_add_f32_e32 v9, v141, v9
	v_exp_f32_e32 v143, v143
	v_add_f32_e32 v9, v125, v9
	v_exp_f32_e32 v127, v127
	v_add_f32_e32 v9, v142, v9
	v_add_f32_e32 v9, v126, v9
	v_add_f32_e32 v9, v143, v9
	v_add_f32_e32 v9, v127, v9
	v_add_f32_e32 v161, v161, v9
	v_cvt_pk_bf16_f32 v128, v128, v129
	v_cvt_pk_bf16_f32 v129, v130, v131
	v_cvt_pk_bf16_f32 v130, v132, v133
	v_cvt_pk_bf16_f32 v131, v134, v135
	v_cvt_pk_bf16_f32 v132, v136, v137
	v_cvt_pk_bf16_f32 v133, v138, v139
	v_cvt_pk_bf16_f32 v134, v140, v141
	v_cvt_pk_bf16_f32 v135, v142, v143
	v_cvt_pk_bf16_f32 v112, v112, v113
	v_cvt_pk_bf16_f32 v113, v114, v115
	v_cvt_pk_bf16_f32 v114, v116, v117
	v_cvt_pk_bf16_f32 v115, v118, v119
	v_cvt_pk_bf16_f32 v116, v120, v121
	v_cvt_pk_bf16_f32 v117, v122, v123
	v_cvt_pk_bf16_f32 v118, v124, v125
	v_cvt_pk_bf16_f32 v119, v126, v127
	s_cmp_lg_u32 s19, 0
	s_cbranch_scc1 .Lpp_x1
	s_waitcnt vmcnt(0)

.Lpp_a1_done:
	ds_read_b64_tr_b16 v[136:137], v166 offset:49152
	ds_read_b64_tr_b16 v[138:139], v158 offset:49152
	ds_read_b64_tr_b16 v[140:141], v167 offset:49152
	ds_read_b64_tr_b16 v[142:143], v160 offset:49152
	ds_read_b64_tr_b16 v[120:121], v168 offset:49152
	ds_read_b64_tr_b16 v[122:123], v162 offset:49152
	ds_read_b64_tr_b16 v[124:125], v169 offset:49152
	ds_read_b64_tr_b16 v[126:127], v163 offset:49152
	s_setprio 2
	s_and_b64 vcc, exec, s[42:43]
	s_cbranch_vccnz .LBB0_1196
	ds_read_b128 v[0:3], v154
	ds_read_b128 v[4:7], v154 offset:8192
	ds_read_b128 v[174:177], v155
	ds_read_b128 v[178:181], v155 offset:8192
	ds_read_b128 v[186:189], v156
	ds_read_b128 v[190:193], v156 offset:8192
	ds_read_b128 v[226:229], v157
	ds_read_b128 v[230:233], v157 offset:8192
	s_waitcnt lgkmcnt(6)
	v_mfma_f32_32x32x16_bf16 v[96:111], v[0:3], v[238:241], 0
	v_mfma_f32_32x32x16_bf16 v[80:95], v[4:7], v[238:241], 0
	s_waitcnt lgkmcnt(4)
	v_mfma_f32_32x32x16_bf16 v[96:111], v[174:177], v[242:245], v[96:111]
	v_mfma_f32_32x32x16_bf16 v[80:95], v[178:181], v[242:245], v[80:95]
	s_waitcnt lgkmcnt(2)
	v_mfma_f32_32x32x16_bf16 v[96:111], v[186:189], v[246:249], v[96:111]
	v_mfma_f32_32x32x16_bf16 v[80:95], v[190:193], v[246:249], v[80:95]
	s_waitcnt lgkmcnt(0)
	v_mfma_f32_32x32x16_bf16 v[96:111], v[226:229], v[234:237], v[96:111]
	v_mfma_f32_32x32x16_bf16 v[80:95], v[230:233], v[234:237], v[80:95]
.LBB0_1196:
	ds_read_b64_tr_b16 v[178:179], v166 offset:53248
	ds_read_b64_tr_b16 v[180:181], v158 offset:53248
	ds_read_b64_tr_b16 v[182:183], v167 offset:53248
	ds_read_b64_tr_b16 v[184:185], v160 offset:53248
	ds_read_b64_tr_b16 v[186:187], v168 offset:53248
	ds_read_b64_tr_b16 v[188:189], v162 offset:53248
	ds_read_b64_tr_b16 v[190:191], v169 offset:53248
	ds_read_b64_tr_b16 v[192:193], v163 offset:53248
	s_waitcnt lgkmcnt(14)
	s_nop 0
	v_mfma_f32_32x32x16_bf16 v[48:63], v[136:139], v[128:131], v[48:63]
	s_waitcnt lgkmcnt(12)
	v_mfma_f32_32x32x16_bf16 v[64:79], v[140:143], v[128:131], v[64:79]
	s_waitcnt lgkmcnt(10)
	v_mfma_f32_32x32x16_bf16 v[32:47], v[120:123], v[128:131], v[32:47]
	s_waitcnt lgkmcnt(8)
	v_mfma_f32_32x32x16_bf16 v[16:31], v[124:127], v[128:131], v[16:31]
	ds_read_b64_tr_b16 v[0:1], v166 offset:57344
	ds_read_b64_tr_b16 v[2:3], v158 offset:57344
	ds_read_b64_tr_b16 v[4:5], v167 offset:57344
	ds_read_b64_tr_b16 v[6:7], v160 offset:57344
	ds_read_b64_tr_b16 v[10:11], v168 offset:57344
	ds_read_b64_tr_b16 v[12:13], v162 offset:57344
	ds_read_b64_tr_b16 v[174:175], v169 offset:57344
	ds_read_b64_tr_b16 v[176:177], v163 offset:57344
	s_waitcnt lgkmcnt(14)
	s_nop 0
	v_mfma_f32_32x32x16_bf16 v[48:63], v[178:181], v[132:135], v[48:63]
	s_waitcnt lgkmcnt(12)
	v_mfma_f32_32x32x16_bf16 v[64:79], v[182:185], v[132:135], v[64:79]
	s_waitcnt lgkmcnt(10)
	v_mfma_f32_32x32x16_bf16 v[32:47], v[186:189], v[132:135], v[32:47]
	s_waitcnt lgkmcnt(8)
	v_mfma_f32_32x32x16_bf16 v[16:31], v[190:193], v[132:135], v[16:31]
	ds_read_b64_tr_b16 v[178:179], v166 offset:61440
	ds_read_b64_tr_b16 v[180:181], v158 offset:61440
	ds_read_b64_tr_b16 v[182:183], v167 offset:61440
	ds_read_b64_tr_b16 v[184:185], v160 offset:61440
	ds_read_b64_tr_b16 v[186:187], v168 offset:61440
	ds_read_b64_tr_b16 v[188:189], v162 offset:61440
	ds_read_b64_tr_b16 v[170:171], v169 offset:61440
	ds_read_b64_tr_b16 v[172:173], v163 offset:61440
	s_waitcnt lgkmcnt(14)
	s_nop 0
	v_mfma_f32_32x32x16_bf16 v[48:63], v[0:3], v[112:115], v[48:63]
	s_waitcnt lgkmcnt(12)
	v_mfma_f32_32x32x16_bf16 v[64:79], v[4:7], v[112:115], v[64:79]
	s_waitcnt lgkmcnt(10)
	v_mfma_f32_32x32x16_bf16 v[32:47], v[10:13], v[112:115], v[32:47]
	s_waitcnt lgkmcnt(8)
	v_mfma_f32_32x32x16_bf16 v[16:31], v[174:177], v[112:115], v[16:31]
	s_cmp_eq_u32 s19, 0
	s_waitcnt lgkmcnt(0)
	s_cbranch_scc1 .Lpp_y1
	s_waitcnt vmcnt(0)
.Lpp_y1:
	s_barrier
	s_setprio 0
	s_waitcnt lgkmcnt(6)
	v_mfma_f32_32x32x16_bf16 v[48:63], v[178:181], v[116:119], v[48:63]
	s_waitcnt lgkmcnt(4)
	v_mfma_f32_32x32x16_bf16 v[64:79], v[182:185], v[116:119], v[64:79]
	s_waitcnt lgkmcnt(2)
	v_mfma_f32_32x32x16_bf16 v[32:47], v[186:189], v[116:119], v[32:47]
	s_waitcnt lgkmcnt(0)
	v_mfma_f32_32x32x16_bf16 v[16:31], v[170:173], v[116:119], v[16:31]
